# residual GEMM: unit after an epilogue enters through a peeled pair of super-phases whose waits do not drain the epilogue stores
# baseline (speedup 1.0000x reference)
; #define GETLANE() int lane; asm volatile("v_mbcnt_lo_u32_b32 %0, -1, 0\n\tv_mbcnt_hi_u32_b32 %0, -1, %0" : "=v"(lane)); const int tid = wave * 64 + lane
;     __device__ __forceinline__ bool next(int i, pg8::Unit& u) const {
;         const int L = i * G + c;
;         if (L < n_lat) {
;             const int wgid = (L & 7) * (n_lat >> 3) + (L >> 3), nig = 8 * nN, w = wgid % nig;
;             u.pm = (((wgid / nig) ^ (ksplit >> 8)) * 8 + (w & 7)) | (ntfull << 16); u.pn = w >> 3; return true; }
;         const int q = L - n_lat; if (q >= n_ctx) return false;
;         const int ksp = ksplit & 0xff, ks = q % ksp, rest = q / ksp; u.pn = (rest % nN) | (ks << 16) | (ksp > 1 ? (1 << 30) : 0); u.pm = (128 + rest / nN) | ((ntfull / ksp) << 16); return true;
; __global__ void __launch_bounds__(NTHR) fwd_megakernel(Args a_unused) {
;     ...
;             else if (j == 2 || j == 9 || j == 12) {
;                 GETLANE(); (void)lane;
;                 const bf16_t* A = j == 9 ? XN : (const bf16_t*)(ws + OFF_HFF);
;                 const bf16_t* Bt = (const bf16_t*)(wb + (j == 2 ? W_FFN1_OUT : (j == 9 ? W_OUT : W_FFN2_OUT)));
;                 const int Kd = j == 9 ? D : DFF;
;                 pg8::Gemm g{A, Bt, MTOT, D, Kd}; CtxOrder S; S.init(D, Kd, G, bid, nctx, j == 9 ? 4 : 11, j == 9 ? 0 : 1);
;                 EpiResid E{hl, hc, modl + (j == 2 ? 2 : (j == 9 ? 5 : 8)) * 1024, j == 9 ? 1.0f : 0.5f}; pg8::gemm_phase<EpiResid, CtxOrder, true, true>(lds, g, S, E, tid); }
.LBB0_37:
	s_mov_b32 s14, s62
	v_writelane_b32 v254, s14, 52
	s_and_b64 vcc, exec, s[20:21]
	s_nop 0
	v_writelane_b32 v254, s15, 53
	s_cbranch_vccz .LBB0_75
	s_mov_b32 s91, 0
	s_cmp_eq_u32 s87, 9
	s_cselect_b64 s[20:21], -1, 0
	v_readlane_b32 s12, v254, 48
	v_mbcnt_lo_u32_b32 v14, -1, 0
	v_mbcnt_hi_u32_b32 v14, -1, v14
	s_nop 1
	v_lshl_add_u32 v1, s12, 6, v14
	s_and_b64 s[12:13], s[20:21], exec
	s_movk_i32 s12, 0x400
	s_cselect_b32 s47, 4, 11
	s_cselect_b32 s16, s12, 0xb00
	s_mul_i32 s12, s46, s47
	s_cselect_b32 s28, 4, 0x10b
	s_lshl_b32 s48, s12, 2
	v_readfirstlane_b32 s29, v1
	s_cmpk_gt_i32 s89, 0x1ff
	s_mov_b64 s[12:13], -1
	s_cbranch_scc0 .LBB0_41
	s_add_i32 s14, s89, 0xfffffe00
	s_mov_b64 s[12:13], 0
	s_cmp_ge_u32 s14, s48
	s_mov_b64 s[14:15], 0
	s_cbranch_scc1 .LBB0_41
	v_cvt_f32_ubyte0_e32 v3, s47
	v_rcp_iflag_f32_e32 v4, v3
	v_cvt_f32_ubyte0_e32 v2, s89
	s_lshr_b32 s26, s16, 6
	v_mul_f32_e32 v5, v2, v4
	v_trunc_f32_e32 v5, v5
	v_fma_f32 v2, -v5, v3, v2
	v_cvt_u32_f32_e32 v5, v5
	v_cmp_ge_f32_e64 s[14:15], |v2|, v3
	s_cmp_lg_u64 s[14:15], 0
	v_cvt_f32_ubyte0_e32 v2, s26
	v_readfirstlane_b32 s27, v5
	s_addc_u32 s14, s27, 0
	s_mul_i32 s15, s14, s47
	v_mul_f32_e32 v4, v2, v4
	s_sub_i32 s15, s89, s15
	v_trunc_f32_e32 v4, v4
	s_and_b32 s15, s15, 0xff
	v_fma_f32 v2, -v4, v3, v2
	v_cvt_u32_f32_e32 v4, v4
	s_and_b32 s27, s14, 3
	s_lshl_b32 s15, s15, 16
	s_lshr_b32 s14, s14, 2
	s_or_b32 s15, s15, s27
	s_bitset1_b32 s14, 7
	s_or_b32 s73, s15, 2.0
	s_and_b32 s27, s14, 0xbf
	v_cmp_ge_f32_e64 s[14:15], |v2|, v3
	v_readfirstlane_b32 s26, v4
	s_cmp_lg_u64 s[14:15], 0
	s_addc_u32 s14, s26, 0
	s_and_b32 s14, s14, 63
	s_lshl_b32 s14, s14, 16
	s_or_b32 s76, s14, s27
	s_mov_b64 s[14:15], -1

; #define PG8_STAGE(bufoff, gbase, voff) do { _Pragma("unroll") for (int _i = 0; _i < 2; ++_i) \
;         __builtin_amdgcn_global_load_lds((const unsigned*)((const char*)(gbase) + (voff)[_i]), (PG8_LAS unsigned*)(lds + (bufoff) + ldsw + _i * 8192), 16, 0, 0); } while (0)
; #define PG8_LDA(dst, b, h) do { _Pragma("unroll") for (int m = 0; m < 4; ++m) _Pragma("unroll") for (int k = 0; k < 2; ++k) dst[m][k] = *(const PG8_LAS bf16x8*)(lds + PG8_SA(b, h) + aoff + m * 2048 + k * 1024); } while (0)
; #define PG8_LDB(dst, b, h) do { _Pragma("unroll") for (int n = 0; n < 2; ++n) _Pragma("unroll") for (int k = 0; k < 2; ++k) dst[n][k] = *(const PG8_LAS bf16x8*)(lds + PG8_SB(b, h) + boff + n * 2048 + k * 1024); } while (0)
; #define PG8_WAIT_V(n) asm volatile("s_waitcnt vmcnt(" #n ")" ::: "memory")
; #define PG8_WAIT_L(n) asm volatile("s_waitcnt lgkmcnt(" #n ")" ::: "memory")
; #define PG8_BAR __builtin_amdgcn_s_barrier()
; #define PG8_SCHED __builtin_amdgcn_sched_barrier(0)
; template <class Epi, class Sched, bool ALIGN_EPI = false, bool SP2 = false>
; __device__ __forceinline__ void gemm_phase(PG8_LAS unsigned char* lds, const Gemm g, const Sched& S, const Epi& E, const int tid_in) {
;     ...
;             PG8_LDB(B0, 0, 0); PG8_LDB(B1, 0, 1); PG8_SCHED; PG8_LDA(At, 0, 0); PG8_STAGE(PG8_SA(1, 1), a1 + hstep, voffA);
;             PG8_WAIT_V(8); PG8_WAIT_L(0); PG8_BAR; PG8_MMA(0, 0, At, B0); PG8_MMA(0, 1, At, B1); PG8_BAR; PG8_SCHED;
;     ...
; #pragma unroll
;         for (int a = 0; a < 2; ++a)
; #pragma unroll
;             for (int b = 0; b < 2; ++b)
; #pragma unroll
;                 for (int m = 0; m < 4; ++m)
; #pragma unroll
;                     for (int n = 0; n < 2; ++n) acc[a][b][m][n] = (f32x4){0.f, 0.f, 0.f, 0.f};
;         cur = nxt; cA = nA; cB = nB; ++ui;
.LBB0_57:
	s_add_i32 s44, s16, -2
	s_add_u32 s40, s40, 0x80
	s_addc_u32 s41, s41, 0
	s_add_u32 s45, s42, 0x100
	v_mov_b32_e32 v2, 0
	s_addc_u32 s77, s43, 0
	s_mov_b32 s42, 0
	v_mov_b32_e32 v3, v2
	v_mov_b32_e32 v4, v2
	v_mov_b32_e32 v5, v2
	v_mov_b32_e32 v6, v2
	v_mov_b32_e32 v7, v2
	v_mov_b32_e32 v8, v2
	v_mov_b32_e32 v9, v2
	v_mov_b32_e32 v18, v2
	v_mov_b32_e32 v19, v2
	v_mov_b32_e32 v20, v2
	v_mov_b32_e32 v21, v2
	v_mov_b32_e32 v22, v2
	v_mov_b32_e32 v23, v2
	v_mov_b32_e32 v24, v2
	v_mov_b32_e32 v25, v2
	v_mov_b32_e32 v34, v2
	v_mov_b32_e32 v35, v2
	v_mov_b32_e32 v36, v2
	v_mov_b32_e32 v37, v2
	v_mov_b32_e32 v38, v2
	v_mov_b32_e32 v39, v2
	v_mov_b32_e32 v40, v2
	v_mov_b32_e32 v41, v2
	v_mov_b32_e32 v50, v2
	v_mov_b32_e32 v51, v2
	v_mov_b32_e32 v52, v2
	v_mov_b32_e32 v53, v2
	v_mov_b32_e32 v54, v2
	v_mov_b32_e32 v55, v2
	v_mov_b32_e32 v56, v2
	v_mov_b32_e32 v57, v2
	v_mov_b32_e32 v10, v2
	v_mov_b32_e32 v11, v2
	v_mov_b32_e32 v12, v2
	v_mov_b32_e32 v13, v2
	v_mov_b32_e32 v14, v2
	v_mov_b32_e32 v15, v2
	v_mov_b32_e32 v16, v2
	v_mov_b32_e32 v17, v2
	v_mov_b32_e32 v26, v2
	v_mov_b32_e32 v27, v2
	v_mov_b32_e32 v28, v2
	v_mov_b32_e32 v29, v2
	v_mov_b32_e32 v30, v2
	v_mov_b32_e32 v31, v2
	v_mov_b32_e32 v32, v2
	v_mov_b32_e32 v33, v2
	v_mov_b32_e32 v42, v2
	v_mov_b32_e32 v43, v2
	v_mov_b32_e32 v44, v2
	v_mov_b32_e32 v45, v2
	v_mov_b32_e32 v46, v2
	v_mov_b32_e32 v47, v2
	v_mov_b32_e32 v48, v2
	v_mov_b32_e32 v49, v2
	v_mov_b32_e32 v58, v2
	v_mov_b32_e32 v59, v2
	v_mov_b32_e32 v60, v2
	v_mov_b32_e32 v61, v2
	v_mov_b32_e32 v62, v2
	v_mov_b32_e32 v63, v2
	v_mov_b32_e32 v64, v2
	v_mov_b32_e32 v65, v2
	v_mov_b32_e32 v66, v2
	v_mov_b32_e32 v67, v2
	v_mov_b32_e32 v68, v2
	v_mov_b32_e32 v69, v2
	v_mov_b32_e32 v70, v2
	v_mov_b32_e32 v71, v2
	v_mov_b32_e32 v72, v2
	v_mov_b32_e32 v73, v2
	v_mov_b32_e32 v82, v2
	v_mov_b32_e32 v83, v2
	v_mov_b32_e32 v84, v2
	v_mov_b32_e32 v85, v2
	v_mov_b32_e32 v86, v2
	v_mov_b32_e32 v87, v2
	v_mov_b32_e32 v88, v2
	v_mov_b32_e32 v89, v2
	v_mov_b32_e32 v98, v2
	v_mov_b32_e32 v99, v2
	v_mov_b32_e32 v100, v2
	v_mov_b32_e32 v101, v2
	v_mov_b32_e32 v102, v2
	v_mov_b32_e32 v103, v2
	v_mov_b32_e32 v104, v2
	v_mov_b32_e32 v105, v2
	v_mov_b32_e32 v114, v2
	v_mov_b32_e32 v115, v2
	v_mov_b32_e32 v116, v2
	v_mov_b32_e32 v117, v2
	v_mov_b32_e32 v118, v2
	v_mov_b32_e32 v119, v2
	v_mov_b32_e32 v120, v2
	v_mov_b32_e32 v121, v2
	v_mov_b32_e32 v74, v2
	v_mov_b32_e32 v75, v2
	v_mov_b32_e32 v76, v2
	v_mov_b32_e32 v77, v2
	v_mov_b32_e32 v78, v2
	v_mov_b32_e32 v79, v2
	v_mov_b32_e32 v80, v2
	v_mov_b32_e32 v81, v2
	v_mov_b32_e32 v90, v2
	v_mov_b32_e32 v91, v2
	v_mov_b32_e32 v92, v2
	v_mov_b32_e32 v93, v2
	v_mov_b32_e32 v94, v2
	v_mov_b32_e32 v95, v2
	v_mov_b32_e32 v96, v2
	v_mov_b32_e32 v97, v2
	v_mov_b32_e32 v106, v2
	v_mov_b32_e32 v107, v2
	v_mov_b32_e32 v108, v2
	v_mov_b32_e32 v109, v2
	v_mov_b32_e32 v110, v2
	v_mov_b32_e32 v111, v2
	v_mov_b32_e32 v112, v2
	v_mov_b32_e32 v113, v2
	v_mov_b32_e32 v122, v2
	v_mov_b32_e32 v123, v2
	v_mov_b32_e32 v124, v2
	v_mov_b32_e32 v125, v2
	v_mov_b32_e32 v126, v2
	v_mov_b32_e32 v127, v2
	v_mov_b32_e32 v128, v2
	v_mov_b32_e32 v129, v2
	s_cmp_eq_u32 s91, 1
	s_cbranch_scc0 .LBB0_58
	s_add_i32 s78, s42, 2
	s_add_u32 s79, s40, 0x80
	s_addc_u32 s43, s41, 0
	s_add_i32 s93, 0, 0x10000
	s_cmp_eq_u32 s44, s42
	s_cselect_b32 s43, s29, s43
	s_cselect_b32 s42, s28, s79
	v_add_u32_e32 v139, s93, v167
	s_cselect_b32 s95, s35, s77
	s_cselect_b32 s94, s34, s45
	s_add_i32 s79, 0, 0x14000
	ds_read_b128 v[146:149], v139
	ds_read_b128 v[150:153], v139 offset:1024
	ds_read_b128 v[154:157], v139 offset:2048
	ds_read_b128 v[158:161], v139 offset:3072
	v_add_u32_e32 v139, s79, v167
	ds_read_b128 v[162:165], v139
	ds_read_b128 v[170:173], v139 offset:1024
	ds_read_b128 v[174:177], v139 offset:2048
	ds_read_b128 v[178:181], v139 offset:3072
	v_lshl_add_u64 v[218:219], s[40:41], 0, v[142:143]
	s_add_i32 m0, s55, 0xc000
	ds_read_b128 v[182:185], v168
	ds_read_b128 v[186:189], v168 offset:1024
	ds_read_b128 v[192:195], v168 offset:2048
	ds_read_b128 v[196:199], v168 offset:3072
	ds_read_b128 v[200:203], v168 offset:4096
	ds_read_b128 v[230:233], v168 offset:5120
	ds_read_b128 v[234:237], v168 offset:6144
	ds_read_b128 v[238:241], v168 offset:7168
	global_load_lds_dwordx4 v[218:219], off
	v_lshl_add_u64 v[218:219], s[40:41], 0, v[144:145]
	s_add_i32 m0, s55, 0xe000
	s_nop 0
	global_load_lds_dwordx4 v[218:219], off
	s_waitcnt vmcnt(40)
	s_waitcnt lgkmcnt(0)
	s_barrier
; #define PG8_STAGE(bufoff, gbase, voff) do { _Pragma("unroll") for (int _i = 0; _i < 2; ++_i) \
;         __builtin_amdgcn_global_load_lds((const unsigned*)((const char*)(gbase) + (voff)[_i]), (PG8_LAS unsigned*)(lds + (bufoff) + ldsw + _i * 8192), 16, 0, 0); } while (0)
; #define PG8_LDA(dst, b, h) do { _Pragma("unroll") for (int m = 0; m < 4; ++m) _Pragma("unroll") for (int k = 0; k < 2; ++k) dst[m][k] = *(const PG8_LAS bf16x8*)(lds + PG8_SA(b, h) + aoff + m * 2048 + k * 1024); } while (0)
; #define PG8_WAIT_V(n) asm volatile("s_waitcnt vmcnt(" #n ")" ::: "memory")
; #define PG8_WAIT_L(n) asm volatile("s_waitcnt lgkmcnt(" #n ")" ::: "memory")
; #define PG8_BAR __builtin_amdgcn_s_barrier()
; #define PG8_SCHED __builtin_amdgcn_sched_barrier(0)
; template <class Epi, class Sched, bool ALIGN_EPI = false, bool SP2 = false>
; __device__ __forceinline__ void gemm_phase(PG8_LAS unsigned char* lds, const Gemm g, const Sched& S, const Epi& E, const int tid_in) {
;     ...
;             PG8_WAIT_V(8); PG8_WAIT_L(0); PG8_BAR; PG8_MMA(0, 0, At, B0); PG8_MMA(0, 1, At, B1); PG8_BAR; PG8_SCHED;
;             PG8_LDA(At, 0, 1); PG8_STAGE(PG8_SB(0, 0), b2, voffB); PG8_STAGE(PG8_SB(0, 1), b2 + hstep, voffB); PG8_STAGE(PG8_SA(0, 0), a2, voffA);
;             PG8_WAIT_V(8); PG8_WAIT_L(0); PG8_BAR; PG8_MMA(1, 0, At, B0); PG8_MMA(1, 1, At, B1); PG8_BAR; PG8_SCHED;
	s_setprio 1
	s_waitcnt lgkmcnt(0)
	v_mfma_f32_16x16x32_f16 v[126:129], v[146:149], v[182:185], v[126:129]
	v_mfma_f32_16x16x32_f16 v[122:125], v[154:157], v[182:185], v[122:125]
	v_mfma_f32_16x16x32_f16 v[110:113], v[146:149], v[192:195], v[110:113]
	v_mfma_f32_16x16x32_f16 v[106:109], v[154:157], v[192:195], v[106:109]
	v_mfma_f32_16x16x32_f16 v[94:97], v[146:149], v[200:203], v[94:97]
	v_mfma_f32_16x16x32_f16 v[90:93], v[154:157], v[200:203], v[90:93]
	v_mfma_f32_16x16x32_f16 v[78:81], v[146:149], v[234:237], v[78:81]
	v_mfma_f32_16x16x32_f16 v[74:77], v[154:157], v[234:237], v[74:77]
	v_mfma_f32_16x16x32_f16 v[126:129], v[150:153], v[186:189], v[126:129]
	v_mfma_f32_16x16x32_f16 v[122:125], v[158:161], v[186:189], v[122:125]
	v_mfma_f32_16x16x32_f16 v[110:113], v[150:153], v[196:199], v[110:113]
	v_mfma_f32_16x16x32_f16 v[106:109], v[158:161], v[196:199], v[106:109]
	v_mfma_f32_16x16x32_f16 v[94:97], v[150:153], v[230:233], v[94:97]
	v_mfma_f32_16x16x32_f16 v[90:93], v[158:161], v[230:233], v[90:93]
	v_mfma_f32_16x16x32_f16 v[78:81], v[150:153], v[238:241], v[78:81]
	v_mfma_f32_16x16x32_f16 v[74:77], v[158:161], v[238:241], v[74:77]
	s_setprio 0
	s_setprio 1
	v_mfma_f32_16x16x32_f16 v[118:121], v[162:165], v[182:185], v[118:121]
	v_mfma_f32_16x16x32_f16 v[114:117], v[174:177], v[182:185], v[114:117]
	v_mfma_f32_16x16x32_f16 v[102:105], v[162:165], v[192:195], v[102:105]
	v_mfma_f32_16x16x32_f16 v[98:101], v[174:177], v[192:195], v[98:101]
	v_mfma_f32_16x16x32_f16 v[86:89], v[162:165], v[200:203], v[86:89]
	v_mfma_f32_16x16x32_f16 v[82:85], v[174:177], v[200:203], v[82:85]
	v_mfma_f32_16x16x32_f16 v[70:73], v[162:165], v[234:237], v[70:73]
	v_mfma_f32_16x16x32_f16 v[66:69], v[174:177], v[234:237], v[66:69]
	v_mfma_f32_16x16x32_f16 v[118:121], v[170:173], v[186:189], v[118:121]
	v_mfma_f32_16x16x32_f16 v[114:117], v[178:181], v[186:189], v[114:117]
	v_mfma_f32_16x16x32_f16 v[102:105], v[170:173], v[196:199], v[102:105]
	v_mfma_f32_16x16x32_f16 v[98:101], v[178:181], v[196:199], v[98:101]
	v_mfma_f32_16x16x32_f16 v[86:89], v[170:173], v[230:233], v[86:89]
	v_mfma_f32_16x16x32_f16 v[82:85], v[178:181], v[230:233], v[82:85]
	v_mfma_f32_16x16x32_f16 v[70:73], v[170:173], v[238:241], v[70:73]
	v_mfma_f32_16x16x32_f16 v[66:69], v[178:181], v[238:241], v[66:69]
	s_setprio 0
	s_barrier
	s_add_i32 s93, s93, s54
	v_lshl_add_u64 v[218:219], s[94:95], 0, v[132:133]
	s_mov_b32 m0, s93
	ds_read_b128 v[182:185], v168 offset:16384
	ds_read_b128 v[186:189], v168 offset:17408
	ds_read_b128 v[192:195], v168 offset:18432
	ds_read_b128 v[196:199], v168 offset:19456
	ds_read_b128 v[200:203], v168 offset:20480
	ds_read_b128 v[230:233], v168 offset:21504
	ds_read_b128 v[234:237], v168 offset:22528
	ds_read_b128 v[238:241], v168 offset:23552
	global_load_lds_dwordx4 v[218:219], off
	s_add_i32 m0, s93, 0x2000
	v_lshl_add_u64 v[220:221], s[94:95], 0, v[136:137]
	s_add_u32 s94, s94, s12
	s_addc_u32 s95, s95, 0
	s_add_i32 s79, s79, s54
	global_load_lds_dwordx4 v[220:221], off
	v_lshl_add_u64 v[222:223], s[94:95], 0, v[132:133]
	s_mov_b32 m0, s79
	v_lshl_add_u64 v[224:225], s[94:95], 0, v[136:137]
	global_load_lds_dwordx4 v[222:223], off
	s_add_i32 m0, s79, 0x2000
	v_lshl_add_u64 v[242:243], s[42:43], 0, v[130:131]
	global_load_lds_dwordx4 v[224:225], off
	s_mov_b32 m0, s55
	v_lshl_add_u64 v[244:245], s[42:43], 0, v[134:135]
	global_load_lds_dwordx4 v[242:243], off
	s_mov_b32 m0, s56
	s_nop 0
	global_load_lds_dwordx4 v[244:245], off
	s_waitcnt vmcnt(40)
	s_waitcnt lgkmcnt(0)
	s_barrier
	s_setprio 1
	s_waitcnt lgkmcnt(0)
	v_mfma_f32_16x16x32_f16 v[62:65], v[146:149], v[182:185], v[62:65]
	v_mfma_f32_16x16x32_f16 v[58:61], v[154:157], v[182:185], v[58:61]
	v_mfma_f32_16x16x32_f16 v[46:49], v[146:149], v[192:195], v[46:49]
	v_mfma_f32_16x16x32_f16 v[42:45], v[154:157], v[192:195], v[42:45]
	v_mfma_f32_16x16x32_f16 v[30:33], v[146:149], v[200:203], v[30:33]
	v_mfma_f32_16x16x32_f16 v[26:29], v[154:157], v[200:203], v[26:29]
	v_mfma_f32_16x16x32_f16 v[14:17], v[146:149], v[234:237], v[14:17]
	v_mfma_f32_16x16x32_f16 v[10:13], v[154:157], v[234:237], v[10:13]
	v_mfma_f32_16x16x32_f16 v[62:65], v[150:153], v[186:189], v[62:65]
	v_mfma_f32_16x16x32_f16 v[58:61], v[158:161], v[186:189], v[58:61]
	v_mfma_f32_16x16x32_f16 v[46:49], v[150:153], v[196:199], v[46:49]
	v_mfma_f32_16x16x32_f16 v[42:45], v[158:161], v[196:199], v[42:45]
	v_mfma_f32_16x16x32_f16 v[30:33], v[150:153], v[230:233], v[30:33]
	v_mfma_f32_16x16x32_f16 v[26:29], v[158:161], v[230:233], v[26:29]
	v_mfma_f32_16x16x32_f16 v[14:17], v[150:153], v[238:241], v[14:17]
	v_mfma_f32_16x16x32_f16 v[10:13], v[158:161], v[238:241], v[10:13]
	s_setprio 0
	s_setprio 1
	v_mfma_f32_16x16x32_f16 v[54:57], v[162:165], v[182:185], v[54:57]
	v_mfma_f32_16x16x32_f16 v[50:53], v[174:177], v[182:185], v[50:53]
	v_mfma_f32_16x16x32_f16 v[38:41], v[162:165], v[192:195], v[38:41]
	v_mfma_f32_16x16x32_f16 v[34:37], v[174:177], v[192:195], v[34:37]
	v_mfma_f32_16x16x32_f16 v[22:25], v[162:165], v[200:203], v[22:25]
	v_mfma_f32_16x16x32_f16 v[18:21], v[174:177], v[200:203], v[18:21]
	v_mfma_f32_16x16x32_f16 v[6:9], v[162:165], v[234:237], v[6:9]
	v_mfma_f32_16x16x32_f16 v[2:5], v[174:177], v[234:237], v[2:5]
	v_mfma_f32_16x16x32_f16 v[54:57], v[170:173], v[186:189], v[54:57]
	v_mfma_f32_16x16x32_f16 v[50:53], v[178:181], v[186:189], v[50:53]
	v_mfma_f32_16x16x32_f16 v[38:41], v[170:173], v[196:199], v[38:41]
	v_mfma_f32_16x16x32_f16 v[34:37], v[178:181], v[196:199], v[34:37]
	v_mfma_f32_16x16x32_f16 v[22:25], v[170:173], v[230:233], v[22:25]
	v_mfma_f32_16x16x32_f16 v[18:21], v[178:181], v[230:233], v[18:21]
	v_mfma_f32_16x16x32_f16 v[6:9], v[170:173], v[238:241], v[6:9]
	v_mfma_f32_16x16x32_f16 v[2:5], v[178:181], v[238:241], v[2:5]
	s_setprio 0
	s_barrier
	s_branch .Lmid_58

; #define PG8_STAGE(bufoff, gbase, voff) do { _Pragma("unroll") for (int _i = 0; _i < 2; ++_i) \
;         __builtin_amdgcn_global_load_lds((const unsigned*)((const char*)(gbase) + (voff)[_i]), (PG8_LAS unsigned*)(lds + (bufoff) + ldsw + _i * 8192), 16, 0, 0); } while (0)
; #define PG8_LDA(dst, b, h) do { _Pragma("unroll") for (int m = 0; m < 4; ++m) _Pragma("unroll") for (int k = 0; k < 2; ++k) dst[m][k] = *(const PG8_LAS bf16x8*)(lds + PG8_SA(b, h) + aoff + m * 2048 + k * 1024); } while (0)
; #define PG8_LDB(dst, b, h) do { _Pragma("unroll") for (int n = 0; n < 2; ++n) _Pragma("unroll") for (int k = 0; k < 2; ++k) dst[n][k] = *(const PG8_LAS bf16x8*)(lds + PG8_SB(b, h) + boff + n * 2048 + k * 1024); } while (0)
; #define PG8_WAIT_V(n) asm volatile("s_waitcnt vmcnt(" #n ")" ::: "memory")
; #define PG8_WAIT_L(n) asm volatile("s_waitcnt lgkmcnt(" #n ")" ::: "memory")
; #define PG8_BAR __builtin_amdgcn_s_barrier()
; #define PG8_SCHED __builtin_amdgcn_sched_barrier(0)
; template <class Epi, class Sched, bool ALIGN_EPI = false, bool SP2 = false>
; __device__ __forceinline__ void gemm_phase(PG8_LAS unsigned char* lds, const Gemm g, const Sched& S, const Epi& E, const int tid_in) {
;     ...
;             PG8_LDB(B0, 1, 0); PG8_LDB(B1, 1, 1); PG8_SCHED; PG8_LDA(At, 1, 0); PG8_STAGE(PG8_SA(0, 1), a2 + hstep, voffA);
;             PG8_WAIT_V(8); PG8_WAIT_L(0); PG8_BAR; PG8_MMA(0, 0, At, B0); PG8_MMA(0, 1, At, B1); PG8_BAR; PG8_SCHED;
.Lmid_58:
	s_add_i32 s79, 0, 0x18000
	v_add_u32_e32 v139, s79, v167
	s_add_i32 s93, 0, 0x1c000
	ds_read_b128 v[146:149], v139
	ds_read_b128 v[150:153], v139 offset:1024
	ds_read_b128 v[154:157], v139 offset:2048
	ds_read_b128 v[158:161], v139 offset:3072
	v_add_u32_e32 v139, s93, v167
	ds_read_b128 v[162:165], v139
	ds_read_b128 v[170:173], v139 offset:1024
	ds_read_b128 v[174:177], v139 offset:2048
	ds_read_b128 v[178:181], v139 offset:3072
	s_add_u32 s42, s42, s12
	s_addc_u32 s43, s43, 0
	s_mov_b32 m0, s57
	v_lshl_add_u64 v[246:247], s[42:43], 0, v[130:131]
	ds_read_b128 v[182:185], v168 offset:32768
	ds_read_b128 v[186:189], v168 offset:33792
	ds_read_b128 v[192:195], v168 offset:34816
	ds_read_b128 v[196:199], v168 offset:35840
	ds_read_b128 v[200:203], v168 offset:36864
	ds_read_b128 v[230:233], v168 offset:37888
	ds_read_b128 v[234:237], v168 offset:38912
	ds_read_b128 v[238:241], v168 offset:39936
	global_load_lds_dwordx4 v[246:247], off
	v_lshl_add_u64 v[246:247], s[42:43], 0, v[134:135]
	s_mov_b32 m0, s58
	s_nop 0
	global_load_lds_dwordx4 v[246:247], off
	s_waitcnt vmcnt(8)
	s_waitcnt lgkmcnt(0)
	s_barrier
	s_setprio 1
	s_waitcnt lgkmcnt(0)
	v_mfma_f32_16x16x32_f16 v[126:129], v[146:149], v[182:185], v[126:129]
	v_mfma_f32_16x16x32_f16 v[122:125], v[154:157], v[182:185], v[122:125]
	v_mfma_f32_16x16x32_f16 v[110:113], v[146:149], v[192:195], v[110:113]
	v_mfma_f32_16x16x32_f16 v[106:109], v[154:157], v[192:195], v[106:109]
	v_mfma_f32_16x16x32_f16 v[94:97], v[146:149], v[200:203], v[94:97]
	v_mfma_f32_16x16x32_f16 v[90:93], v[154:157], v[200:203], v[90:93]
	v_mfma_f32_16x16x32_f16 v[78:81], v[146:149], v[234:237], v[78:81]
	v_mfma_f32_16x16x32_f16 v[74:77], v[154:157], v[234:237], v[74:77]
	v_mfma_f32_16x16x32_f16 v[126:129], v[150:153], v[186:189], v[126:129]
	v_mfma_f32_16x16x32_f16 v[122:125], v[158:161], v[186:189], v[122:125]
	v_mfma_f32_16x16x32_f16 v[110:113], v[150:153], v[196:199], v[110:113]
	v_mfma_f32_16x16x32_f16 v[106:109], v[158:161], v[196:199], v[106:109]
	v_mfma_f32_16x16x32_f16 v[94:97], v[150:153], v[230:233], v[94:97]
	v_mfma_f32_16x16x32_f16 v[90:93], v[158:161], v[230:233], v[90:93]
	v_mfma_f32_16x16x32_f16 v[78:81], v[150:153], v[238:241], v[78:81]
	v_mfma_f32_16x16x32_f16 v[74:77], v[158:161], v[238:241], v[74:77]
	s_setprio 0
	s_setprio 1
	v_mfma_f32_16x16x32_f16 v[118:121], v[162:165], v[182:185], v[118:121]
	v_mfma_f32_16x16x32_f16 v[114:117], v[174:177], v[182:185], v[114:117]
	v_mfma_f32_16x16x32_f16 v[102:105], v[162:165], v[192:195], v[102:105]
	v_mfma_f32_16x16x32_f16 v[98:101], v[174:177], v[192:195], v[98:101]
	v_mfma_f32_16x16x32_f16 v[86:89], v[162:165], v[200:203], v[86:89]
	v_mfma_f32_16x16x32_f16 v[82:85], v[174:177], v[200:203], v[82:85]
	v_mfma_f32_16x16x32_f16 v[70:73], v[162:165], v[234:237], v[70:73]
	v_mfma_f32_16x16x32_f16 v[66:69], v[174:177], v[234:237], v[66:69]
	v_mfma_f32_16x16x32_f16 v[118:121], v[170:173], v[186:189], v[118:121]
	v_mfma_f32_16x16x32_f16 v[114:117], v[178:181], v[186:189], v[114:117]
	v_mfma_f32_16x16x32_f16 v[102:105], v[170:173], v[196:199], v[102:105]
	v_mfma_f32_16x16x32_f16 v[98:101], v[178:181], v[196:199], v[98:101]
	v_mfma_f32_16x16x32_f16 v[86:89], v[170:173], v[230:233], v[86:89]
	v_mfma_f32_16x16x32_f16 v[82:85], v[178:181], v[230:233], v[82:85]
	v_mfma_f32_16x16x32_f16 v[70:73], v[170:173], v[238:241], v[70:73]
	v_mfma_f32_16x16x32_f16 v[66:69], v[178:181], v[238:241], v[66:69]
	s_setprio 0
	s_barrier
; #define PG8_STAGE(bufoff, gbase, voff) do { _Pragma("unroll") for (int _i = 0; _i < 2; ++_i) \
;         __builtin_amdgcn_global_load_lds((const unsigned*)((const char*)(gbase) + (voff)[_i]), (PG8_LAS unsigned*)(lds + (bufoff) + ldsw + _i * 8192), 16, 0, 0); } while (0)
; #define PG8_LDA(dst, b, h) do { _Pragma("unroll") for (int m = 0; m < 4; ++m) _Pragma("unroll") for (int k = 0; k < 2; ++k) dst[m][k] = *(const PG8_LAS bf16x8*)(lds + PG8_SA(b, h) + aoff + m * 2048 + k * 1024); } while (0)
; #define PG8_WAIT_V(n) asm volatile("s_waitcnt vmcnt(" #n ")" ::: "memory")
; #define PG8_WAIT_L(n) asm volatile("s_waitcnt lgkmcnt(" #n ")" ::: "memory")
; #define PG8_BAR __builtin_amdgcn_s_barrier()
; #define PG8_SCHED __builtin_amdgcn_sched_barrier(0)
; template <class Epi, class Sched, bool ALIGN_EPI = false, bool SP2 = false>
; __device__ __forceinline__ void gemm_phase(PG8_LAS unsigned char* lds, const Gemm g, const Sched& S, const Epi& E, const int tid_in) {
;     ...
;         for (int t = 0; t < nt; t += 2) {
;             const bool last = (t == nt - 2);
;             const char* a1 = cA + (size_t)(t + 1) * kstep;
;             const char* a2 = last ? nA : cA + (size_t)(t + 2) * kstep; const char* b2 = last ? nB : cB + (size_t)(t + 2) * kstep;
;     ...
;             PG8_LDA(At, 1, 1); PG8_STAGE(PG8_SB(1, 0), b3, voffB); PG8_STAGE(PG8_SB(1, 1), b3 + hstep, voffB); PG8_STAGE(PG8_SA(1, 0), a3, voffA);
;             PG8_WAIT_V(8); PG8_WAIT_L(0); PG8_BAR; PG8_MMA(1, 0, At, B0); PG8_MMA(1, 1, At, B1); PG8_BAR; PG8_SCHED;
	s_add_i32 s42, s79, s54
	v_lshl_add_u64 v[218:219], v[218:219], 0, s[24:25]
	s_mov_b32 m0, s42
	ds_read_b128 v[182:185], v168 offset:49152
	ds_read_b128 v[186:189], v168 offset:50176
	ds_read_b128 v[192:195], v168 offset:51200
	ds_read_b128 v[196:199], v168 offset:52224
	ds_read_b128 v[200:203], v168 offset:53248
	ds_read_b128 v[230:233], v168 offset:54272
	ds_read_b128 v[234:237], v168 offset:55296
	ds_read_b128 v[238:241], v168 offset:56320
	global_load_lds_dwordx4 v[218:219], off
	v_lshl_add_u64 v[218:219], v[220:221], 0, s[24:25]
	s_add_i32 m0, s42, 0x2000
	s_add_i32 s42, s93, s54
	global_load_lds_dwordx4 v[218:219], off
	v_lshl_add_u64 v[218:219], v[222:223], 0, s[24:25]
	s_mov_b32 m0, s42
	s_nop 0
	global_load_lds_dwordx4 v[218:219], off
	v_lshl_add_u64 v[218:219], v[224:225], 0, s[24:25]
	s_add_i32 m0, s42, 0x2000
	s_nop 0
	global_load_lds_dwordx4 v[218:219], off
	v_lshl_add_u64 v[218:219], v[242:243], 0, s[24:25]
	s_mov_b32 m0, s61
	s_nop 0
	global_load_lds_dwordx4 v[218:219], off
	v_lshl_add_u64 v[218:219], v[244:245], 0, s[24:25]
	s_mov_b32 m0, s62
	s_nop 0
	global_load_lds_dwordx4 v[218:219], off
	s_waitcnt vmcnt(8)
	s_waitcnt lgkmcnt(0)
	s_barrier
	s_setprio 1
	s_waitcnt lgkmcnt(0)
	v_mfma_f32_16x16x32_f16 v[62:65], v[146:149], v[182:185], v[62:65]
	v_mfma_f32_16x16x32_f16 v[58:61], v[154:157], v[182:185], v[58:61]
	v_mfma_f32_16x16x32_f16 v[46:49], v[146:149], v[192:195], v[46:49]
	v_mfma_f32_16x16x32_f16 v[42:45], v[154:157], v[192:195], v[42:45]
	v_mfma_f32_16x16x32_f16 v[30:33], v[146:149], v[200:203], v[30:33]
	v_mfma_f32_16x16x32_f16 v[26:29], v[154:157], v[200:203], v[26:29]
	v_mfma_f32_16x16x32_f16 v[14:17], v[146:149], v[234:237], v[14:17]
	v_mfma_f32_16x16x32_f16 v[10:13], v[154:157], v[234:237], v[10:13]
	v_mfma_f32_16x16x32_f16 v[62:65], v[150:153], v[186:189], v[62:65]
	v_mfma_f32_16x16x32_f16 v[58:61], v[158:161], v[186:189], v[58:61]
	v_mfma_f32_16x16x32_f16 v[46:49], v[150:153], v[196:199], v[46:49]
	v_mfma_f32_16x16x32_f16 v[42:45], v[158:161], v[196:199], v[42:45]
	v_mfma_f32_16x16x32_f16 v[30:33], v[150:153], v[230:233], v[30:33]
	v_mfma_f32_16x16x32_f16 v[26:29], v[158:161], v[230:233], v[26:29]
	v_mfma_f32_16x16x32_f16 v[14:17], v[150:153], v[238:241], v[14:17]
	v_mfma_f32_16x16x32_f16 v[10:13], v[158:161], v[238:241], v[10:13]
	s_setprio 0
	s_setprio 1
	v_mfma_f32_16x16x32_f16 v[54:57], v[162:165], v[182:185], v[54:57]
	v_mfma_f32_16x16x32_f16 v[50:53], v[174:177], v[182:185], v[50:53]
	v_mfma_f32_16x16x32_f16 v[38:41], v[162:165], v[192:195], v[38:41]
	v_mfma_f32_16x16x32_f16 v[34:37], v[174:177], v[192:195], v[34:37]
	v_mfma_f32_16x16x32_f16 v[22:25], v[162:165], v[200:203], v[22:25]
	v_mfma_f32_16x16x32_f16 v[18:21], v[174:177], v[200:203], v[18:21]
	v_mfma_f32_16x16x32_f16 v[6:9], v[162:165], v[234:237], v[6:9]
	v_mfma_f32_16x16x32_f16 v[2:5], v[174:177], v[234:237], v[2:5]
	v_mfma_f32_16x16x32_f16 v[54:57], v[170:173], v[186:189], v[54:57]
	v_mfma_f32_16x16x32_f16 v[50:53], v[178:181], v[186:189], v[50:53]
	v_mfma_f32_16x16x32_f16 v[38:41], v[170:173], v[196:199], v[38:41]
	v_mfma_f32_16x16x32_f16 v[34:37], v[178:181], v[196:199], v[34:37]
	v_mfma_f32_16x16x32_f16 v[22:25], v[170:173], v[230:233], v[22:25]
	v_mfma_f32_16x16x32_f16 v[18:21], v[178:181], v[230:233], v[18:21]
	v_mfma_f32_16x16x32_f16 v[6:9], v[170:173], v[238:241], v[6:9]
	v_mfma_f32_16x16x32_f16 v[2:5], v[178:181], v[238:241], v[2:5]
	s_setprio 0
	s_barrier
	s_add_u32 s40, s40, 0x100
	s_addc_u32 s41, s41, 0
	s_add_u32 s45, s45, 0x100
	s_addc_u32 s77, s77, 0
	s_cmp_ge_i32 s78, s16
	s_mov_b32 s42, s78
	s_cbranch_scc0 .LBB0_58
	s_movk_i32 s77, 0x2fff
	s_mov_b32 s78, 0x3fb8aa3b
	s_and_b64 vcc, exec, s[20:21]
	s_cbranch_vccz .LBB0_61

;     __device__ __forceinline__ void operator()(const pg8::f32x4 (&acc)[2][2][4][2], const pg8::Unit& uu, int wr, int wc, int fr, int fq) const {
;         asm volatile("" : "+v"(fr), "+v"(fq));
;         const int upm = uu.pm & 0xffff, upn = uu.pn & 0xffff, unt = uu.pm >> 16; (void)unt;
;         float* base; const float* g;
;         if (upm < 128) { base = hl + (size_t)upm * 256 * D; g = gate + (upm >> 5) * 9216; } else { base = hc + (size_t)(upm - 128) * 256 * D; g = gate + 4 * 9216; }
;         const int col0 = upn * 256 + wc * 32 + 8 * fq;
;         pg8::f32x4 gv[2][2];
; #pragma unroll
;         for (int bj = 0; bj < 2; ++bj)
; #pragma unroll
;             for (int n = 0; n < 2; ++n) gv[bj][n] = *(const pg8::f32x4*)(g + col0 + bj * 128 + 4 * n) * coef;
;         if (!((uu.pn >> 30) & 1)) {
; #pragma unroll
;             for (int ai = 0; ai < 2; ++ai)
; #pragma unroll
;                 for (int m = 0; m < 4; ++m) { float* rowp = base + (size_t)(wr * 64 + fr + ai * 128 + m * 16) * D + col0;
; #pragma unroll
;                     for (int bj = 0; bj < 2; ++bj)
; #pragma unroll
;                         for (int n = 0; n < 2; ++n) { pg8::f32x4* p = (pg8::f32x4*)(rowp + bj * 128 + 4 * n); *p = *p + gv[bj][n] * acc[ai][bj][m][n]; } }
;         } else {
;             float* pb = hc + (OFF_PART - OFF_HC) / 4 + ((size_t)((uu.pn >> 16) & 0xff) * 1024 + (size_t)(upm - 128) * 256) * D;
; #pragma unroll
;             for (int ai = 0; ai < 2; ++ai)
; #pragma unroll
;                 for (int m = 0; m < 4; ++m) { float* rowp = pb + (size_t)(wr * 64 + fr + ai * 128 + m * 16) * D + col0;
; #pragma unroll
;                     for (int bj = 0; bj < 2; ++bj)
; #pragma unroll
;                         for (int n = 0; n < 2; ++n) *(pg8::f32x4*)(rowp + bj * 128 + 4 * n) = gv[bj][n] * acc[ai][bj][m][n]; }
;         }
.LBB0_65:
	s_mov_b32 s91, 1
	s_lshl_b32 s16, s73, 8
	s_and_b32 s16, s16, 0xffff00
	s_or_b32 s16, s16, s64
	v_lshl_add_u32 v162, v139, 3, s16
	v_ashrrev_i32_e32 v163, 31, v162
	v_lshl_add_u64 v[154:155], v[162:163], 2, s[44:45]
	global_load_dwordx4 v[146:149], v[154:155], off
	global_load_dwordx4 v[150:153], v[154:155], off offset:16
	global_load_dwordx4 v[170:173], v[154:155], off offset:512
	global_load_dwordx4 v[174:177], v[154:155], off offset:528
	v_mov_b32_e32 v139, v138
	s_bitcmp1_b32 s73, 30
	s_mov_b64 s[44:45], -1
	s_waitcnt vmcnt(0)
	v_pk_mul_f32 v[158:159], v[138:139], v[148:149]
	v_pk_mul_f32 v[160:161], v[140:141], v[146:147]
	v_pk_mul_f32 v[154:155], v[138:139], v[152:153]
	v_pk_mul_f32 v[156:157], v[140:141], v[150:151]
	v_pk_mul_f32 v[150:151], v[138:139], v[172:173]
	v_pk_mul_f32 v[152:153], v[140:141], v[170:171]
	v_pk_mul_f32 v[146:147], v[138:139], v[176:177]
	v_pk_mul_f32 v[148:149], v[140:141], v[174:175]
	s_cbranch_scc0 .LBB0_71
	s_mov_b32 s43, s17
	s_lshl_b64 s[42:43], s[42:43], 20
	s_add_u32 s16, s67, s42
	s_addc_u32 s43, s68, s43
	s_lshl_b32 s42, s73, 6
	s_and_b32 s42, s42, 0x3fc00000
	s_add_u32 s42, s16, s42
	v_add_u32_e32 v164, s63, v169
	s_addc_u32 s43, s43, 0
	v_ashrrev_i32_e32 v165, 31, v164
	v_lshl_add_u64 v[170:171], v[162:163], 2, s[42:43]
	v_lshlrev_b64 v[164:165], 12, v[164:165]
	v_lshl_add_u64 v[164:165], v[170:171], 0, v[164:165]
	s_brev_b32 s16, 31
	s_brev_b32 s42, 31
	v_add_co_u32_e32 v176, vcc, s16, v164
	s_mov_b32 s43, -1
	v_pk_mul_f32 v[172:173], v[128:129], v[158:159]
	v_pk_mul_f32 v[170:171], v[126:127], v[160:161]
	v_addc_co_u32_e32 v177, vcc, -1, v165, vcc
	v_lshl_add_u64 v[174:175], v[164:165], 0, s[42:43]
	global_store_dwordx4 v[176:177], v[170:173], off
	s_mov_b32 s16, 0xf8010000
	s_mov_b32 s42, 0xf8010000
	v_pk_mul_f32 v[172:173], v[124:125], v[154:155]
	v_pk_mul_f32 v[170:171], v[122:123], v[156:157]
	global_store_dwordx4 v[174:175], v[170:173], off offset:16
	v_add_co_u32_e32 v176, vcc, s16, v164
	s_nop 0
	v_pk_mul_f32 v[172:173], v[120:121], v[150:151]
	v_pk_mul_f32 v[170:171], v[118:119], v[152:153]
	global_store_dwordx4 v[174:175], v[170:173], off offset:512
	s_mov_b32 s43, -1
	v_addc_co_u32_e32 v177, vcc, -1, v165, vcc
	v_pk_mul_f32 v[172:173], v[116:117], v[146:147]
	v_pk_mul_f32 v[170:171], v[114:115], v[148:149]
	global_store_dwordx4 v[174:175], v[170:173], off offset:528
	v_lshl_add_u64 v[174:175], v[164:165], 0, s[42:43]
	s_mov_b32 s16, 0xf8020000
	v_pk_mul_f32 v[172:173], v[112:113], v[158:159]
	v_pk_mul_f32 v[170:171], v[110:111], v[160:161]
	global_store_dwordx4 v[176:177], v[170:173], off
	s_mov_b32 s42, 0xf8020000
	v_add_co_u32_e32 v176, vcc, s16, v164
	v_pk_mul_f32 v[172:173], v[108:109], v[154:155]
	v_pk_mul_f32 v[170:171], v[106:107], v[156:157]
	global_store_dwordx4 v[174:175], v[170:173], off offset:16
	s_mov_b32 s43, -1
	v_addc_co_u32_e32 v177, vcc, -1, v165, vcc
	v_pk_mul_f32 v[172:173], v[104:105], v[150:151]
	v_pk_mul_f32 v[170:171], v[102:103], v[152:153]
	global_store_dwordx4 v[174:175], v[170:173], off offset:512
	s_mov_b32 s16, 0xf8030000
	s_nop 0
	v_pk_mul_f32 v[172:173], v[100:101], v[146:147]
	v_pk_mul_f32 v[170:171], v[98:99], v[148:149]
	global_store_dwordx4 v[174:175], v[170:173], off offset:528
	v_lshl_add_u64 v[174:175], v[164:165], 0, s[42:43]
	s_mov_b32 s42, 0xf8030000
	v_pk_mul_f32 v[172:173], v[96:97], v[158:159]
	v_pk_mul_f32 v[170:171], v[94:95], v[160:161]
	global_store_dwordx4 v[176:177], v[170:173], off
	v_add_co_u32_e32 v176, vcc, s16, v164
	s_nop 0
	v_pk_mul_f32 v[172:173], v[92:93], v[154:155]
	v_pk_mul_f32 v[170:171], v[90:91], v[156:157]
	global_store_dwordx4 v[174:175], v[170:173], off offset:16
	s_mov_b32 s43, -1
	v_addc_co_u32_e32 v177, vcc, -1, v165, vcc
	v_pk_mul_f32 v[172:173], v[88:89], v[150:151]
	v_pk_mul_f32 v[170:171], v[86:87], v[152:153]
	global_store_dwordx4 v[174:175], v[170:173], off offset:512
	s_mov_b32 s16, 0xf8080000
	s_nop 0
	v_pk_mul_f32 v[172:173], v[84:85], v[146:147]
	v_pk_mul_f32 v[170:171], v[82:83], v[148:149]
	global_store_dwordx4 v[174:175], v[170:173], off offset:528
;     __device__ __forceinline__ void operator()(const pg8::f32x4 (&acc)[2][2][4][2], const pg8::Unit& uu, int wr, int wc, int fr, int fq) const {
;     ...
;             float* pb = hc + (OFF_PART - OFF_HC) / 4 + ((size_t)((uu.pn >> 16) & 0xff) * 1024 + (size_t)(upm - 128) * 256) * D;
; #pragma unroll
;             for (int ai = 0; ai < 2; ++ai)
; #pragma unroll
;                 for (int m = 0; m < 4; ++m) { float* rowp = pb + (size_t)(wr * 64 + fr + ai * 128 + m * 16) * D + col0;
; #pragma unroll
;                     for (int bj = 0; bj < 2; ++bj)
; #pragma unroll
;                         for (int n = 0; n < 2; ++n) *(pg8::f32x4*)(rowp + bj * 128 + 4 * n) = gv[bj][n] * acc[ai][bj][m][n]; }
	v_lshl_add_u64 v[174:175], v[164:165], 0, s[42:43]
	s_mov_b32 s42, 0xf8080000
	v_pk_mul_f32 v[172:173], v[80:81], v[158:159]
	v_pk_mul_f32 v[170:171], v[78:79], v[160:161]
	global_store_dwordx4 v[176:177], v[170:173], off
	v_add_co_u32_e32 v176, vcc, s16, v164
	s_nop 0
	v_pk_mul_f32 v[172:173], v[76:77], v[154:155]
	v_pk_mul_f32 v[170:171], v[74:75], v[156:157]
	global_store_dwordx4 v[174:175], v[170:173], off offset:16
	s_mov_b32 s43, -1
	v_addc_co_u32_e32 v177, vcc, -1, v165, vcc
	v_pk_mul_f32 v[172:173], v[72:73], v[150:151]
	v_pk_mul_f32 v[170:171], v[70:71], v[152:153]
	global_store_dwordx4 v[174:175], v[170:173], off offset:512
	s_mov_b32 s16, 0xf8090000
	s_nop 0
	v_pk_mul_f32 v[172:173], v[68:69], v[146:147]
	v_pk_mul_f32 v[170:171], v[66:67], v[148:149]
	global_store_dwordx4 v[174:175], v[170:173], off offset:528
	v_lshl_add_u64 v[174:175], v[164:165], 0, s[42:43]
	s_mov_b32 s42, 0xf8090000
	v_pk_mul_f32 v[172:173], v[64:65], v[158:159]
	v_pk_mul_f32 v[170:171], v[62:63], v[160:161]
	global_store_dwordx4 v[176:177], v[170:173], off
	v_add_co_u32_e32 v176, vcc, s16, v164
	s_nop 0
	v_pk_mul_f32 v[172:173], v[60:61], v[154:155]
	v_pk_mul_f32 v[170:171], v[58:59], v[156:157]
	global_store_dwordx4 v[174:175], v[170:173], off offset:16
	s_mov_b32 s43, -1
	v_addc_co_u32_e32 v177, vcc, -1, v165, vcc
	v_pk_mul_f32 v[172:173], v[56:57], v[150:151]
	v_pk_mul_f32 v[170:171], v[54:55], v[152:153]
	global_store_dwordx4 v[174:175], v[170:173], off offset:512
	s_mov_b32 s16, 0xf80a0000
	s_nop 0
	v_pk_mul_f32 v[172:173], v[52:53], v[146:147]
	v_pk_mul_f32 v[170:171], v[50:51], v[148:149]
	global_store_dwordx4 v[174:175], v[170:173], off offset:528
	v_lshl_add_u64 v[174:175], v[164:165], 0, s[42:43]
	s_mov_b32 s42, 0xf80a0000
	v_pk_mul_f32 v[172:173], v[48:49], v[158:159]
	v_pk_mul_f32 v[170:171], v[46:47], v[160:161]
	global_store_dwordx4 v[176:177], v[170:173], off
	v_add_co_u32_e32 v176, vcc, s16, v164
	s_nop 0
	v_pk_mul_f32 v[172:173], v[44:45], v[154:155]
	v_pk_mul_f32 v[170:171], v[42:43], v[156:157]
	global_store_dwordx4 v[174:175], v[170:173], off offset:16
	s_mov_b32 s43, -1
	v_addc_co_u32_e32 v177, vcc, -1, v165, vcc
	v_pk_mul_f32 v[172:173], v[40:41], v[150:151]
	v_pk_mul_f32 v[170:171], v[38:39], v[152:153]
	global_store_dwordx4 v[174:175], v[170:173], off offset:512
	s_mov_b32 s16, 0xf80b0000
	s_nop 0
	v_pk_mul_f32 v[172:173], v[36:37], v[146:147]
	v_pk_mul_f32 v[170:171], v[34:35], v[148:149]
	global_store_dwordx4 v[174:175], v[170:173], off offset:528
	v_lshl_add_u64 v[174:175], v[164:165], 0, s[42:43]
	s_mov_b32 s42, 0xf80b0000
	v_pk_mul_f32 v[172:173], v[32:33], v[158:159]
	v_pk_mul_f32 v[170:171], v[30:31], v[160:161]
	global_store_dwordx4 v[176:177], v[170:173], off
	s_mov_b32 s43, -1
	s_nop 0
	v_pk_mul_f32 v[172:173], v[28:29], v[154:155]
	v_pk_mul_f32 v[170:171], v[26:27], v[156:157]
	global_store_dwordx4 v[174:175], v[170:173], off offset:16
	s_nop 1
	v_pk_mul_f32 v[172:173], v[24:25], v[150:151]
	v_pk_mul_f32 v[170:171], v[22:23], v[152:153]
	global_store_dwordx4 v[174:175], v[170:173], off offset:512
	s_nop 1
	v_pk_mul_f32 v[172:173], v[20:21], v[146:147]
	v_pk_mul_f32 v[170:171], v[18:19], v[148:149]
	global_store_dwordx4 v[174:175], v[170:173], off offset:528
	v_lshl_add_u64 v[174:175], v[164:165], 0, s[42:43]
	v_add_co_u32_e32 v164, vcc, s16, v164
	v_pk_mul_f32 v[172:173], v[16:17], v[158:159]
	v_pk_mul_f32 v[170:171], v[14:15], v[160:161]
	v_addc_co_u32_e32 v165, vcc, -1, v165, vcc
	global_store_dwordx4 v[164:165], v[170:173], off
	s_nop 1
	v_pk_mul_f32 v[172:173], v[12:13], v[154:155]
	v_pk_mul_f32 v[170:171], v[10:11], v[156:157]
	global_store_dwordx4 v[174:175], v[170:173], off offset:16
	s_nop 1
	v_pk_mul_f32 v[172:173], v[8:9], v[150:151]
	v_pk_mul_f32 v[170:171], v[6:7], v[152:153]
	global_store_dwordx4 v[174:175], v[170:173], off offset:512
	s_nop 1
	v_pk_mul_f32 v[172:173], v[4:5], v[146:147]
	v_pk_mul_f32 v[170:171], v[2:3], v[148:149]
	global_store_dwordx4 v[174:175], v[170:173], off offset:528
	s_cbranch_execz .LBB0_72
